# P8 final norm: rows dealt to waves 0-3 of all 256 workgroups instead of 8 waves of workgroups 0-127
# speedup vs baseline: 1.0013x; 1.0013x over previous
; DI float bflo(unsigned u) { return __uint_as_float(u << 16); }
; DI float bfhi(unsigned u) { return __uint_as_float(u & 0xffff0000u); }
; DI void final_norm(const Params& P, int G, int wave, int lane, float* dst) {
;     const int gw = blockIdx.x * 8 + wave, NGW = G * 8;
;     const bf16_t* h1b = (const bf16_t*)(P.ws + WS_H1B);
;     for (int m = MP + gw; m < MT; m += NGW) {
;         f32x4 v[4]; float s = 0.f;
; #pragma unroll
;         for (int j = 0; j < 4; ++j) { const u32x2 hb = *(const u32x2*)(h1b + (size_t)m * DM + 4 * lane + 256 * j); v[j] = (f32x4){bflo(hb.x), bfhi(hb.x), bflo(hb.y), bfhi(hb.y)}; }
;         const bf16_t* sl = (const bf16_t*)(P.ws + WS_SLAB) + (size_t)(m - MP) * DM + 4 * lane;
.LBB0_1154:
	s_or_b64 exec, exec, s[0:1]
	v_readlane_b32 s64, v255, 13
	v_readlane_b32 s2, v255, 14
	s_lshl_b32 s64, s64, 8
	s_lshr_b32 s2, s2, 3
	s_add_i32 s64, s64, s2
	s_add_i32 s2, s64, 0x4000
	s_cmpk_gt_i32 s2, 0x43ff
	s_waitcnt lgkmcnt(0)
	s_barrier
	s_cbranch_scc1 .LBB0_1157
	v_lshlrev_b32_e32 v0, 2, v175
	v_and_b32_e32 v2, 0xfc, v0
	v_lshlrev_b32_e32 v0, 1, v2
	v_mov_b32_e32 v1, 0
	v_lshl_add_u64 v[4:5], s[6:7], 0, v[0:1]
	v_and_b32_e32 v0, 64, v201
	v_add_u32_e32 v0, 64, v0
	v_xor_b32_e32 v3, 1, v201
	v_cmp_lt_i32_e32 vcc, v3, v0
	s_ashr_i32 s3, s2, 31
	s_lshl_b64 s[0:1], s[2:3], 11
	v_cndmask_b32_e32 v3, v201, v3, vcc
	v_lshlrev_b32_e32 v20, 2, v3
	v_xor_b32_e32 v3, 2, v201
	v_cmp_lt_i32_e32 vcc, v3, v0
	v_and_b32_e32 v10, 63, v175
	s_add_u32 s0, s68, s0
	v_cndmask_b32_e32 v3, v201, v3, vcc
	v_lshlrev_b32_e32 v21, 2, v3
	v_xor_b32_e32 v3, 4, v201
	v_cmp_lt_i32_e32 vcc, v3, v0
	s_addc_u32 s1, s69, s1
	s_ashr_i32 s67, s66, 31
	v_cndmask_b32_e32 v3, v201, v3, vcc
	v_lshlrev_b32_e32 v22, 2, v3
	v_xor_b32_e32 v3, 8, v201
	v_cmp_lt_i32_e32 vcc, v3, v0
	s_lshl_b64 s[2:3], s[2:3], 12
	s_mov_b32 s4, 0x200000
	v_cndmask_b32_e32 v3, v201, v3, vcc
	v_cmp_lt_i32_e32 vcc, v209, v0
	v_lshlrev_b32_e32 v23, 2, v3
	s_mov_b32 s5, 0x400000
	v_cndmask_b32_e32 v3, v201, v209, vcc
	v_cmp_lt_i32_e32 vcc, v254, v0
	v_lshlrev_b32_e32 v24, 2, v3
	s_mov_b32 s6, 0x600000
	v_cndmask_b32_e32 v0, v201, v254, vcc
	v_lshlrev_b32_e32 v25, 2, v0
	v_lshlrev_b32_e32 v0, 2, v2
	v_lshl_add_u64 v[6:7], s[60:61], 0, v[0:1]
	v_lshlrev_b32_e32 v0, 3, v10
	v_lshl_add_u64 v[2:3], s[0:1], 0, v[0:1]
	s_mov_b64 s[0:1], 0xdc00000
	v_lshl_add_u64 v[8:9], v[2:3], 0, s[0:1]
	s_lshl_b64 s[0:1], s[66:67], 11
	s_add_u32 s2, s62, s2
	v_lshlrev_b32_e32 v0, 4, v10
	s_addc_u32 s3, s63, s3
	v_lshl_add_u64 v[10:11], s[2:3], 0, v[0:1]
	s_lshl_b64 s[2:3], s[66:67], 12
	s_mov_b32 s7, 0x800000
	s_mov_b32 s8, 0xa00000
	s_mov_b32 s9, 0xc00000
	s_mov_b32 s10, 0xe00000
	v_mov_b32_e32 v26, 0x358637bd
